# weight transposes: thread-to-k mapping changed so each store instruction writes 64 contiguous bytes per output row (constants only)
# speedup vs baseline: 1.0241x; 1.0008x over previous
.LBB0_14:
	s_lshr_b32 s3, s2, 8
	v_writelane_b32 v254, s14, 5
	s_and_b32 s2, s14, 0xc0
	v_writelane_b32 v254, s2, 7
	s_nop 0
	v_readlane_b32 s2, v254, 0
	s_lshl_b32 s2, s2, 1
	s_nop 0
	v_writelane_b32 v254, s2, 8
	s_add_i32 s2, s3, s2
	v_writelane_b32 v254, s2, 10
	s_nop 1
	v_writelane_b32 v254, s3, 11
	s_load_dword s2, s[12:13], 0xb8
	s_waitcnt lgkmcnt(0)
	s_lshl_b32 s2, s2, 1
	v_writelane_b32 v254, s2, 12
	s_nop 1
	v_writelane_b32 v254, s3, 13
	v_writelane_b32 v254, s3, 14
	v_writelane_b32 v254, s12, 15
	s_load_dwordx2 s[6:7], s[12:13], 0xb0
	s_mul_i32 s2, s3, 0x12400
	s_add_i32 s91, s2, 16
	v_writelane_b32 v254, s13, 16
	s_waitcnt lgkmcnt(0)
	s_cmp_gt_i32 s6, 0
	s_cselect_b64 s[2:3], -1, 0
	s_cmp_lt_i32 s7, 0
	s_cselect_b64 s[4:5], -1, 0
	s_or_b64 s[2:3], s[2:3], s[4:5]
	s_and_b64 vcc, exec, s[2:3]
	s_cbranch_vccnz .LBB0_66
	v_readlane_b32 s2, v254, 15
	v_readlane_b32 s3, v254, 16
	s_load_dwordx2 s[8:9], s[2:3], 0xa8
	v_readlane_b32 s2, v254, 10
	v_mov_b32_e32 v11, 0
	v_mov_b32_e32 v2, 0
	s_cmpk_gt_i32 s2, 0x7ff
	v_readlane_b32 s3, v254, 11
	s_cbranch_scc1 .LBB0_26
	v_readlane_b32 s2, v254, 15
	v_readlane_b32 s3, v254, 16
	v_mbcnt_lo_u32_b32 v2, -1, v2
	s_load_dwordx2 s[4:5], s[2:3], 0x38
	s_nop 0
	s_load_dwordx2 s[2:3], s[2:3], 0x48
	v_mbcnt_hi_u32_b32 v2, -1, v2
	v_readlane_b32 s6, v254, 7
	v_readlane_b32 s12, v254, 12
	s_waitcnt lgkmcnt(0)
	s_cmp_lg_u64 s[4:5], 0
	v_add_u32_e32 v3, s6, v2
	v_lshlrev_b32_e32 v2, 4, v2
	v_and_b32_e32 v10, 0xf0, v2
	v_and_b32_e32 v2, 48, v2
	v_lshrrev_b32_e32 v2, 1, v2
	v_mul_u32_u24_e32 v4, 0x41, v2
	v_ashrrev_i32_e32 v21, 4, v3
	v_ashrrev_i32_e32 v23, 2, v3
	v_lshlrev_b32_e32 v4, 2, v4
	v_and_b32_e32 v3, -4, v3
	s_movk_i32 s6, 0x104
	v_lshl_add_u64 v[12:13], s[2:3], 0, v[10:11]
	s_cselect_b64 s[2:3], -1, 0
	v_add3_u32 v24, s91, v4, v3
	v_mul_lo_u32 v3, v21, s6
	v_add3_u32 v25, s91, v3, v10
	v_readlane_b32 s6, v254, 10
	v_cndmask_b32_e64 v3, 0, 1, s[2:3]
	v_add_u32_e32 v26, 0x1040, v25
	v_add_u32_e32 v27, 0x2080, v25
	v_add_u32_e32 v28, 0x30c0, v25
	s_lshl_b32 s10, s6, 6
	s_lshl_b32 s11, s12, 6
	v_cmp_ne_u32_e64 s[2:3], 1, v3
	v_lshlrev_b32_e32 v10, 1, v2
	s_mov_b32 s12, s6
	v_readlane_b32 s7, v254, 11
	v_readlane_b32 s13, v254, 13
	s_branch .LBB0_18
.LBB0_17:
	s_waitcnt vmcnt(0)
	v_pk_mul_f32 v[2:3], v[48:49], v[58:59] op_sel_hi:[1,0]
	ds_write2_b32 v28, v2, v3 offset1:1
	v_pk_mul_f32 v[2:3], v[50:51], v[58:59] op_sel_hi:[1,0]
	v_add_u32_e32 v7, 0x2060, v24
	ds_write2_b32 v28, v2, v3 offset0:2 offset1:3
	s_waitcnt lgkmcnt(0)
	s_barrier
	ds_read2_b32 v[2:3], v24 offset1:65
	ds_read2_b32 v[4:5], v7 offset0:8 offset1:73
	ds_read2_b32 v[8:9], v24 offset0:130 offset1:195
	v_add_u32_e32 v18, 0x2460, v24
	s_sub_i32 s7, 0, s7
	s_add_i32 s7, s7, s10
	s_waitcnt lgkmcnt(1)
	v_cvt_pk_bf16_f32 v6, v4, v5
	ds_read2_b32 v[4:5], v7 offset0:138 offset1:203
	v_add_u32_e32 v7, 0x400, v24
	v_cvt_pk_bf16_f32 v2, v2, v3
	s_waitcnt lgkmcnt(1)
	v_cvt_pk_bf16_f32 v3, v8, v9
	ds_read2_b32 v[8:9], v7 offset0:4 offset1:69
	ds_read2_b32 v[14:15], v18 offset0:12 offset1:77
	ds_read2_b32 v[16:17], v7 offset0:134 offset1:199
	ds_read2_b32 v[18:19], v18 offset0:142 offset1:207
	s_waitcnt lgkmcnt(4)
	v_cvt_pk_bf16_f32 v7, v4, v5
	s_add_i32 s10, s10, s11
	s_waitcnt lgkmcnt(3)
	v_cvt_pk_bf16_f32 v4, v8, v9
	s_waitcnt lgkmcnt(2)
	v_cvt_pk_bf16_f32 v8, v14, v15
	v_add_u32_e32 v14, s7, v23
	v_ashrrev_i32_e32 v15, 31, v14
	v_lshlrev_b64 v[14:15], 11, v[14:15]
	v_lshl_add_u64 v[14:15], s[8:9], 0, v[14:15]
	s_ashr_i32 s7, s6, 31
	v_lshl_add_u64 v[14:15], s[6:7], 1, v[14:15]
	v_readlane_b32 s6, v254, 12
	s_add_i32 s12, s12, s6
	s_waitcnt lgkmcnt(1)
	v_cvt_pk_bf16_f32 v5, v16, v17
	s_waitcnt lgkmcnt(0)
	v_cvt_pk_bf16_f32 v9, v18, v19
	v_lshl_add_u64 v[14:15], v[14:15], 0, v[10:11]
	s_cmpk_lt_i32 s12, 0x800
	global_store_dwordx4 v[14:15], v[2:5], off
	v_readlane_b32 s7, v254, 13
	global_store_dwordx4 v[14:15], v[6:9], off offset:64
	s_cbranch_scc0 .LBB0_26

.LBB0_398:
	s_cmp_gt_i32 s6, 3
	s_cselect_b64 s[0:1], -1, 0
	s_cmp_lt_i32 s7, 3
	s_cselect_b64 s[2:3], -1, 0
	s_or_b64 s[0:1], s[0:1], s[2:3]
	s_and_b64 vcc, exec, s[0:1]
	s_cbranch_vccnz .LBB0_481
	v_readlane_b32 s0, v254, 12
	v_readlane_b32 s1, v254, 13
	s_cmpk_lg_i32 s0, 0x200
	s_mov_b64 s[0:1], -1
	s_cbranch_scc0 .LBB0_404
	v_readlane_b32 s0, v254, 10
	v_mov_b32_e32 v1, 0
	v_mov_b32_e32 v0, 0
	s_cmpk_gt_i32 s0, 0x1ff
	v_readlane_b32 s10, v254, 12
	v_readlane_b32 s1, v254, 11
	v_readlane_b32 s11, v254, 13
	s_cbranch_scc1 .LBB0_403
	v_readlane_b32 s2, v254, 15
	v_readlane_b32 s3, v254, 16
	s_load_dwordx2 s[0:1], s[2:3], 0xa8
	s_nop 0
	s_load_dwordx2 s[2:3], s[2:3], 0x60
	v_mbcnt_lo_u32_b32 v0, -1, v0
	v_mbcnt_hi_u32_b32 v0, -1, v0
	v_lshlrev_b32_e32 v7, 4, v0
	v_readlane_b32 s4, v254, 7
	v_and_b32_e32 v12, 48, v7
	v_lshrrev_b32_e32 v12, 1, v12
	s_waitcnt lgkmcnt(0)
	s_add_u32 s0, s0, 0x1000000
	v_add_u32_e32 v6, s4, v0
	v_and_b32_e32 v0, 0xf0, v7
	v_mul_u32_u24_e32 v7, 0x41, v12
	v_ashrrev_i32_e32 v4, 4, v6
	v_lshl_add_u64 v[2:3], s[2:3], 0, v[0:1]
	v_ashrrev_i32_e32 v5, 2, v6
	v_lshlrev_b32_e32 v7, 2, v7
	v_and_b32_e32 v6, -4, v6
	s_movk_i32 s2, 0x104
	v_add3_u32 v6, s91, v7, v6
	v_mul_lo_u32 v7, v4, s2
	v_add3_u32 v7, s91, v7, v0
	v_readlane_b32 s2, v254, 10
	s_addc_u32 s1, s1, 0
	v_add_u32_e32 v8, 0x1040, v7
	v_add_u32_e32 v9, 0x2080, v7
	v_add_u32_e32 v10, 0x30c0, v7
	s_lshl_b32 s6, s2, 6
	s_lshl_b32 s7, s10, 6
	v_lshlrev_b32_e32 v0, 1, v12
	v_add_u32_e32 v11, 0x2060, v6
	v_add_u32_e32 v12, 0x400, v6
	v_add_u32_e32 v13, 0x2460, v6
	s_mov_b32 s8, s2
	v_readlane_b32 s3, v254, 11
.LBB0_402:
	s_ashr_i32 s2, s8, 31
	s_lshr_b32 s2, s2, 28
	s_add_i32 s2, s8, s2
	s_ashr_i32 s3, s2, 4
	s_lshl_b32 s2, s3, 6
	s_lshl_b32 s3, s3, 10
	v_add_u32_e32 v14, s2, v4
	s_sub_i32 s4, s6, s3
	v_add_u32_e32 v16, 16, v14
	s_ashr_i32 s5, s4, 31
	v_ashrrev_i32_e32 v15, 31, v14
	v_add_u32_e32 v18, 32, v14
	v_add_u32_e32 v20, 48, v14
	v_ashrrev_i32_e32 v17, 31, v16
	v_lshl_add_u64 v[22:23], s[4:5], 2, v[2:3]
	v_lshlrev_b64 v[14:15], 12, v[14:15]
	v_ashrrev_i32_e32 v19, 31, v18
	v_ashrrev_i32_e32 v21, 31, v20
	v_lshlrev_b64 v[24:25], 12, v[16:17]
	v_lshl_add_u64 v[14:15], v[22:23], 0, v[14:15]
	v_lshlrev_b64 v[18:19], 12, v[18:19]
	v_lshlrev_b64 v[20:21], 12, v[20:21]
	v_lshl_add_u64 v[30:31], v[22:23], 0, v[24:25]
	s_waitcnt vmcnt(63) expcnt(7) lgkmcnt(15)
	s_barrier
	global_load_dwordx4 v[14:17], v[14:15], off
	v_lshl_add_u64 v[32:33], v[22:23], 0, v[18:19]
	v_lshl_add_u64 v[34:35], v[22:23], 0, v[20:21]
	global_load_dwordx4 v[18:21], v[30:31], off
	global_load_dwordx4 v[22:25], v[32:33], off
	global_load_dwordx4 v[26:29], v[34:35], off
	v_add_u32_e32 v30, s4, v5
	v_ashrrev_i32_e32 v31, 31, v30
	v_lshlrev_b64 v[30:31], 12, v[30:31]
	s_ashr_i32 s3, s2, 31
	v_lshl_add_u64 v[30:31], s[0:1], 0, v[30:31]
	s_add_i32 s8, s8, s10
	s_add_i32 s6, s6, s7
	v_lshl_add_u64 v[30:31], s[2:3], 1, v[30:31]
	s_cmpk_lt_i32 s8, 0x200
	v_lshl_add_u64 v[30:31], v[30:31], 0, v[0:1]
	s_waitcnt vmcnt(3)
	ds_write2_b32 v7, v14, v15 offset1:1
	ds_write2_b32 v7, v16, v17 offset0:2 offset1:3
	s_waitcnt vmcnt(2)
	ds_write2_b32 v8, v18, v19 offset1:1
	ds_write2_b32 v8, v20, v21 offset0:2 offset1:3
	s_waitcnt vmcnt(1)
	ds_write2_b32 v9, v22, v23 offset1:1
	ds_write2_b32 v9, v24, v25 offset0:2 offset1:3
	s_waitcnt vmcnt(0)
	ds_write2_b32 v10, v26, v27 offset1:1
	ds_write2_b32 v10, v28, v29 offset0:2 offset1:3
	s_waitcnt lgkmcnt(0)
	s_barrier
	ds_read2_b32 v[14:15], v6 offset1:65
	ds_read2_b32 v[16:17], v11 offset0:8 offset1:73
	ds_read2_b32 v[20:21], v6 offset0:130 offset1:195
	ds_read2_b32 v[22:23], v11 offset0:138 offset1:203
	ds_read2_b32 v[24:25], v12 offset0:4 offset1:69
	ds_read2_b32 v[26:27], v13 offset0:12 offset1:77
	ds_read2_b32 v[28:29], v12 offset0:134 offset1:199
	ds_read2_b32 v[32:33], v13 offset0:142 offset1:207
	s_waitcnt lgkmcnt(7)
	v_cvt_pk_bf16_f32 v14, v14, v15
	s_waitcnt lgkmcnt(6)
	v_cvt_pk_bf16_f32 v18, v16, v17
	s_waitcnt lgkmcnt(5)
	v_cvt_pk_bf16_f32 v15, v20, v21
	s_waitcnt lgkmcnt(3)
	v_cvt_pk_bf16_f32 v16, v24, v25
	s_waitcnt lgkmcnt(1)
	v_cvt_pk_bf16_f32 v17, v28, v29
	v_cvt_pk_bf16_f32 v19, v22, v23
	v_cvt_pk_bf16_f32 v20, v26, v27
	s_waitcnt lgkmcnt(0)
	v_cvt_pk_bf16_f32 v21, v32, v33
	global_store_dwordx4 v[30:31], v[14:17], off
	global_store_dwordx4 v[30:31], v[18:21], off offset:64
	s_cbranch_scc1 .LBB0_402

.LBB0_404:
	s_and_b64 vcc, exec, s[0:1]
	s_cbranch_vccz .LBB0_410
	v_readlane_b32 s0, v254, 10
	s_and_b32 s0, s0, 7
	s_cmp_gt_u32 s0, 3
	v_readlane_b32 s1, v254, 11
	s_cbranch_scc1 .LBB0_410
	v_readlane_b32 s2, v254, 10
	s_ashr_i32 s1, s2, 1
	s_and_b32 s1, s1, -4
	s_or_b32 s6, s1, s0
	v_mov_b32_e32 v1, 0
	v_mov_b32_e32 v0, 0
	s_cmpk_gt_i32 s6, 0x1ff
	v_readlane_b32 s3, v254, 11
	s_cbranch_scc1 .LBB0_409
	v_readlane_b32 s2, v254, 15
	v_readlane_b32 s3, v254, 16
	s_load_dwordx2 s[0:1], s[2:3], 0xa8
	s_nop 0
	s_load_dwordx2 s[2:3], s[2:3], 0x60
	v_mbcnt_lo_u32_b32 v0, -1, v0
	v_mbcnt_hi_u32_b32 v0, -1, v0
	v_lshlrev_b32_e32 v7, 4, v0
	v_readlane_b32 s4, v254, 7
	v_and_b32_e32 v12, 48, v7
	v_lshrrev_b32_e32 v12, 1, v12
	s_waitcnt lgkmcnt(0)
	s_add_u32 s0, s0, 0x1000000
	v_add_u32_e32 v6, s4, v0
	v_and_b32_e32 v0, 0xf0, v7
	v_mul_u32_u24_e32 v7, 0x41, v12
	v_ashrrev_i32_e32 v4, 4, v6
	v_lshl_add_u64 v[2:3], s[2:3], 0, v[0:1]
	v_ashrrev_i32_e32 v5, 2, v6
	v_lshlrev_b32_e32 v7, 2, v7
	v_and_b32_e32 v6, -4, v6
	s_movk_i32 s2, 0x104
	v_add3_u32 v6, s91, v7, v6
	v_mul_lo_u32 v7, v4, s2
	v_add3_u32 v7, s91, v7, v0
	s_addc_u32 s1, s1, 0
	v_add_u32_e32 v8, 0x1040, v7
	v_add_u32_e32 v9, 0x2080, v7
	v_add_u32_e32 v10, 0x30c0, v7
	s_lshl_b32 s7, s6, 6
	v_lshlrev_b32_e32 v0, 1, v12
	v_add_u32_e32 v11, 0x2060, v6
	v_add_u32_e32 v12, 0x400, v6
	v_add_u32_e32 v13, 0x2460, v6
.LBB0_408:
	s_ashr_i32 s2, s6, 31
	s_lshr_b32 s2, s2, 28
	s_add_i32 s2, s6, s2
	s_ashr_i32 s3, s2, 4
	s_lshl_b32 s2, s3, 6
	s_lshl_b32 s3, s3, 10
	v_add_u32_e32 v14, s2, v4
	s_sub_i32 s4, s7, s3
	v_add_u32_e32 v16, 16, v14
	s_ashr_i32 s5, s4, 31
	v_ashrrev_i32_e32 v15, 31, v14
	v_add_u32_e32 v18, 32, v14
	v_add_u32_e32 v20, 48, v14
	v_ashrrev_i32_e32 v17, 31, v16
	v_lshl_add_u64 v[22:23], s[4:5], 2, v[2:3]
	v_lshlrev_b64 v[14:15], 12, v[14:15]
	v_ashrrev_i32_e32 v19, 31, v18
	v_ashrrev_i32_e32 v21, 31, v20
	v_lshlrev_b64 v[24:25], 12, v[16:17]
	v_lshl_add_u64 v[14:15], v[22:23], 0, v[14:15]
	v_lshlrev_b64 v[18:19], 12, v[18:19]
	v_lshlrev_b64 v[20:21], 12, v[20:21]
	v_lshl_add_u64 v[30:31], v[22:23], 0, v[24:25]
	s_waitcnt vmcnt(63) expcnt(7) lgkmcnt(15)
	s_barrier
	global_load_dwordx4 v[14:17], v[14:15], off
	v_lshl_add_u64 v[32:33], v[22:23], 0, v[18:19]
	v_lshl_add_u64 v[34:35], v[22:23], 0, v[20:21]
	global_load_dwordx4 v[18:21], v[30:31], off
	global_load_dwordx4 v[22:25], v[32:33], off
	global_load_dwordx4 v[26:29], v[34:35], off
	v_add_u32_e32 v30, s4, v5
	v_ashrrev_i32_e32 v31, 31, v30
	v_lshlrev_b64 v[30:31], 12, v[30:31]
	s_ashr_i32 s3, s2, 31
	v_lshl_add_u64 v[30:31], s[0:1], 0, v[30:31]
	s_add_i32 s5, s6, 0x100
	s_addk_i32 s7, 0x4000
	v_lshl_add_u64 v[30:31], s[2:3], 1, v[30:31]
	s_cmpk_lt_i32 s6, 0x100
	s_mov_b32 s6, s5
	v_lshl_add_u64 v[30:31], v[30:31], 0, v[0:1]
	s_waitcnt vmcnt(3)
	ds_write2_b32 v7, v14, v15 offset1:1
	ds_write2_b32 v7, v16, v17 offset0:2 offset1:3
	s_waitcnt vmcnt(2)
	ds_write2_b32 v8, v18, v19 offset1:1
	ds_write2_b32 v8, v20, v21 offset0:2 offset1:3
	s_waitcnt vmcnt(1)
	ds_write2_b32 v9, v22, v23 offset1:1
	ds_write2_b32 v9, v24, v25 offset0:2 offset1:3
	s_waitcnt vmcnt(0)
	ds_write2_b32 v10, v26, v27 offset1:1
	ds_write2_b32 v10, v28, v29 offset0:2 offset1:3
	s_waitcnt lgkmcnt(0)
	s_barrier
	ds_read2_b32 v[14:15], v6 offset1:65
	ds_read2_b32 v[16:17], v11 offset0:8 offset1:73
	ds_read2_b32 v[20:21], v6 offset0:130 offset1:195
	ds_read2_b32 v[22:23], v11 offset0:138 offset1:203
	ds_read2_b32 v[24:25], v12 offset0:4 offset1:69
	ds_read2_b32 v[26:27], v13 offset0:12 offset1:77
	ds_read2_b32 v[28:29], v12 offset0:134 offset1:199
	ds_read2_b32 v[32:33], v13 offset0:142 offset1:207
	s_waitcnt lgkmcnt(7)
	v_cvt_pk_bf16_f32 v14, v14, v15
	s_waitcnt lgkmcnt(6)
	v_cvt_pk_bf16_f32 v18, v16, v17
	s_waitcnt lgkmcnt(5)
	v_cvt_pk_bf16_f32 v15, v20, v21
	s_waitcnt lgkmcnt(3)
	v_cvt_pk_bf16_f32 v16, v24, v25
	s_waitcnt lgkmcnt(1)
	v_cvt_pk_bf16_f32 v17, v28, v29
	v_cvt_pk_bf16_f32 v19, v22, v23
	v_cvt_pk_bf16_f32 v20, v26, v27
	s_waitcnt lgkmcnt(0)
	v_cvt_pk_bf16_f32 v21, v32, v33
	global_store_dwordx4 v[30:31], v[14:17], off
	global_store_dwordx4 v[30:31], v[18:21], off offset:64
	s_cbranch_scc1 .LBB0_408

.LBB0_508:
	s_cmpk_lt_i32 s10, 0x80
	v_readlane_b32 s2, v254, 12
	s_cselect_b64 s[0:1], -1, 0
	v_readlane_b32 s3, v254, 13
	s_cmpk_lt_i32 s2, 0x81
	s_cselect_b64 s[2:3], -1, 0
	s_or_b64 s[0:1], s[2:3], s[0:1]
	s_and_b64 vcc, exec, s[0:1]
	s_cbranch_vccnz .LBB0_546
	v_readlane_b32 s0, v254, 10
	v_readlane_b32 s1, v254, 11
	s_add_i32 s13, s0, 0xffffff80
	v_readlane_b32 s0, v254, 12
	s_add_i32 s12, s0, 0xffffff80
	v_mov_b32_e32 v1, 0
	v_mov_b32_e32 v0, 0
	s_cmpk_gt_u32 s13, 0x3ff
	v_readlane_b32 s1, v254, 13
	s_cbranch_scc1 .LBB0_512
	v_readlane_b32 s14, v254, 15
	v_readlane_b32 s15, v254, 16
	s_load_dwordx2 s[2:3], s[14:15], 0x38
	s_load_dwordx2 s[4:5], s[14:15], 0x78
	v_mbcnt_lo_u32_b32 v0, -1, v0
	v_mbcnt_hi_u32_b32 v0, -1, v0
	v_lshlrev_b32_e32 v7, 4, v0
	v_readlane_b32 s6, v254, 7
	v_and_b32_e32 v12, 48, v7
	v_lshrrev_b32_e32 v12, 1, v12
	s_add_u32 s0, s8, 0x1400000
	v_add_u32_e32 v6, s6, v0
	v_and_b32_e32 v0, 0xf0, v7
	v_mul_u32_u24_e32 v7, 0x41, v12
	v_ashrrev_i32_e32 v4, 4, v6
	s_waitcnt lgkmcnt(0)
	v_lshl_add_u64 v[2:3], s[4:5], 0, v[0:1]
	v_ashrrev_i32_e32 v5, 2, v6
	v_lshlrev_b32_e32 v7, 2, v7
	v_and_b32_e32 v6, -4, v6
	s_movk_i32 s4, 0x104
	v_add3_u32 v6, s91, v7, v6
	v_mul_lo_u32 v7, v4, s4
	s_load_dword s4, s[14:15], 0xb8
	s_addc_u32 s1, s9, 0
	s_add_u32 s2, s2, 0x1000
	s_addc_u32 s3, s3, 0
	v_add3_u32 v7, s91, v7, v0
	s_waitcnt lgkmcnt(0)
	s_lshl_b32 s11, s4, 7
	v_add_u32_e32 v8, 0x1040, v7
	v_add_u32_e32 v9, 0x2080, v7
	v_add_u32_e32 v10, 0x30c0, v7
	s_lshl_b32 s10, s13, 6
	s_addk_i32 s11, 0xe000
	s_mov_b32 s5, 0
	v_lshlrev_b32_e32 v0, 1, v12
	v_add_u32_e32 v11, 0x2060, v6
	v_add_u32_e32 v12, 0x400, v6
	v_add_u32_e32 v13, 0x2460, v6
	s_mov_b32 s14, s13
.LBB0_511:
	s_and_b32 s6, s14, 0xffffffc0
	s_and_b32 s15, s10, 0xfc0
	v_add_u32_e32 v14, s6, v4
	s_lshl_b32 s4, s15, 2
	v_ashrrev_i32_e32 v15, 31, v14
	v_add_u32_e32 v16, 16, v14
	v_add_u32_e32 v20, 32, v14
	v_lshl_add_u64 v[18:19], v[2:3], 0, s[4:5]
	v_add_u32_e32 v22, 48, v14
	v_lshlrev_b64 v[24:25], 14, v[14:15]
	v_ashrrev_i32_e32 v17, 31, v16
	v_ashrrev_i32_e32 v21, 31, v20
	v_lshl_add_u64 v[14:15], v[14:15], 2, s[2:3]
	v_ashrrev_i32_e32 v23, 31, v22
	v_lshl_add_u64 v[24:25], v[18:19], 0, v[24:25]
	v_lshl_add_u64 v[28:29], v[16:17], 2, s[2:3]
	v_lshlrev_b64 v[32:33], 14, v[20:21]
	v_lshl_add_u64 v[20:21], v[20:21], 2, s[2:3]
	s_barrier
	global_load_dword v30, v[14:15], off
	global_load_dword v40, v[28:29], off
	global_load_dword v42, v[20:21], off
	v_lshlrev_b64 v[26:27], 14, v[16:17]
	v_lshlrev_b64 v[34:35], 14, v[22:23]
	v_lshl_add_u64 v[36:37], v[22:23], 2, s[2:3]
	global_load_dwordx4 v[14:17], v[24:25], off
	v_lshl_add_u64 v[38:39], v[18:19], 0, v[26:27]
	v_lshl_add_u64 v[32:33], v[18:19], 0, v[32:33]
	v_lshl_add_u64 v[34:35], v[18:19], 0, v[34:35]
	global_load_dword v44, v[36:37], off
	global_load_dwordx4 v[18:21], v[38:39], off
	global_load_dwordx4 v[22:25], v[32:33], off
	global_load_dwordx4 v[26:29], v[34:35], off
	v_add_u32_e32 v32, s15, v5
	v_ashrrev_i32_e32 v33, 31, v32
	v_lshlrev_b64 v[32:33], 11, v[32:33]
	s_mov_b32 s7, s5
	v_lshl_add_u64 v[32:33], s[0:1], 0, v[32:33]
	s_add_i32 s14, s14, s12
	s_add_i32 s10, s10, s11
	v_lshl_add_u64 v[32:33], s[6:7], 1, v[32:33]
	s_cmpk_lt_i32 s14, 0x400
	v_lshl_add_u64 v[32:33], v[32:33], 0, v[0:1]
	s_waitcnt vmcnt(4)
	v_pk_mul_f32 v[14:15], v[14:15], v[30:31] op_sel_hi:[1,0]
	v_pk_mul_f32 v[16:17], v[16:17], v[30:31] op_sel_hi:[1,0]
	ds_write2_b32 v7, v14, v15 offset1:1
	ds_write2_b32 v7, v16, v17 offset0:2 offset1:3
	s_waitcnt vmcnt(2)
	v_pk_mul_f32 v[14:15], v[18:19], v[40:41] op_sel_hi:[1,0]
	v_pk_mul_f32 v[16:17], v[20:21], v[40:41] op_sel_hi:[1,0]
	s_waitcnt vmcnt(1)
	v_pk_mul_f32 v[18:19], v[22:23], v[42:43] op_sel_hi:[1,0]
	v_pk_mul_f32 v[20:21], v[24:25], v[42:43] op_sel_hi:[1,0]
	s_waitcnt vmcnt(0)
	v_pk_mul_f32 v[22:23], v[26:27], v[44:45] op_sel_hi:[1,0]
	v_pk_mul_f32 v[24:25], v[28:29], v[44:45] op_sel_hi:[1,0]
	ds_write2_b32 v8, v14, v15 offset1:1
	ds_write2_b32 v8, v16, v17 offset0:2 offset1:3
	ds_write2_b32 v9, v18, v19 offset1:1
	ds_write2_b32 v9, v20, v21 offset0:2 offset1:3
	ds_write2_b32 v10, v22, v23 offset1:1
	ds_write2_b32 v10, v24, v25 offset0:2 offset1:3
	s_waitcnt lgkmcnt(0)
	s_barrier
	ds_read2_b32 v[14:15], v6 offset1:65
	ds_read2_b32 v[16:17], v11 offset0:8 offset1:73
	ds_read2_b32 v[20:21], v6 offset0:130 offset1:195
	ds_read2_b32 v[22:23], v11 offset0:138 offset1:203
	ds_read2_b32 v[24:25], v12 offset0:4 offset1:69
	ds_read2_b32 v[26:27], v13 offset0:12 offset1:77
	ds_read2_b32 v[28:29], v12 offset0:134 offset1:199
	ds_read2_b32 v[30:31], v13 offset0:142 offset1:207
	s_waitcnt lgkmcnt(7)
	v_cvt_pk_bf16_f32 v14, v14, v15
	s_waitcnt lgkmcnt(6)
	v_cvt_pk_bf16_f32 v18, v16, v17
	s_waitcnt lgkmcnt(5)
	v_cvt_pk_bf16_f32 v15, v20, v21
	s_waitcnt lgkmcnt(3)
	v_cvt_pk_bf16_f32 v16, v24, v25
	s_waitcnt lgkmcnt(1)
	v_cvt_pk_bf16_f32 v17, v28, v29
	v_cvt_pk_bf16_f32 v19, v22, v23
	v_cvt_pk_bf16_f32 v20, v26, v27
	s_waitcnt lgkmcnt(0)
	v_cvt_pk_bf16_f32 v21, v30, v31
	global_store_dwordx4 v[32:33], v[14:17], off
	global_store_dwordx4 v[32:33], v[18:21], off offset:64
	s_cbranch_scc1 .LBB0_511
.LBB0_512:
	s_cmpk_gt_u32 s13, 0x7f
	s_cbranch_scc1 .LBB0_523
	v_mbcnt_lo_u32_b32 v0, -1, v1
	v_mbcnt_hi_u32_b32 v0, -1, v0
	v_readlane_b32 s6, v254, 7
	v_readlane_b32 s14, v254, 15
	v_readlane_b32 s15, v254, 16
	v_add_u32_e32 v1, s6, v0
	v_lshlrev_b32_e32 v0, 4, v0
	v_and_b32_e32 v8, 0xf0, v0
	v_and_b32_e32 v0, 48, v0
	v_lshrrev_b32_e32 v0, 1, v0
	s_load_dwordx4 s[0:3], s[14:15], 0x68
	v_mul_u32_u24_e32 v2, 0x41, v0
	v_ashrrev_i32_e32 v19, 4, v1
	v_ashrrev_i32_e32 v21, 2, v1
	v_lshlrev_b32_e32 v2, 2, v2
	v_and_b32_e32 v1, -4, v1
	s_movk_i32 s6, 0x104
	v_add3_u32 v22, s91, v2, v1
	v_mul_lo_u32 v1, v19, s6
	s_load_dword s6, s[14:15], 0xb8
	s_add_u32 s4, s8, 0x1c00000
	s_addc_u32 s5, s9, 0
	v_mov_b32_e32 v9, 0
	s_waitcnt lgkmcnt(0)
	s_cmp_lg_u64 s[0:1], 0
	v_lshl_add_u64 v[10:11], s[2:3], 0, v[8:9]
	s_cselect_b64 s[2:3], -1, 0
	v_add3_u32 v23, s91, v1, v8
	s_lshl_b32 s11, s6, 7
	s_lshl_b32 s15, s6, 4
	v_cndmask_b32_e64 v1, 0, 1, s[2:3]
	v_add_u32_e32 v24, 0x1040, v23
	v_add_u32_e32 v25, 0x2080, v23
	v_add_u32_e32 v26, 0x30c0, v23
	s_lshl_b32 s10, s13, 6
	s_addk_i32 s11, 0xe000
	s_lshl_b32 s14, s13, 3
	s_addk_i32 s15, 0xfc00
	s_mov_b32 s7, 0
	v_cmp_ne_u32_e64 s[2:3], 1, v1
	v_lshlrev_b32_e32 v8, 1, v0
	s_mov_b32 s16, s13
	s_branch .LBB0_515
.LBB0_514:
	s_waitcnt vmcnt(0)
	v_pk_mul_f32 v[0:1], v[4:5], v[18:19] op_sel_hi:[1,0]
	ds_write2_b32 v26, v0, v1 offset1:1
	v_pk_mul_f32 v[0:1], v[6:7], v[18:19] op_sel_hi:[1,0]
	v_add_u32_e32 v5, 0x2060, v22
	ds_write2_b32 v26, v0, v1 offset0:2 offset1:3
	s_waitcnt lgkmcnt(0)
	s_barrier
	ds_read2_b32 v[0:1], v22 offset1:65
	ds_read2_b32 v[2:3], v5 offset0:8 offset1:73
	ds_read2_b32 v[6:7], v22 offset0:130 offset1:195
	v_add_u32_e32 v16, 0x2460, v22
	s_lshl_b32 s6, s17, 1
	s_add_i32 s16, s16, s12
	s_waitcnt lgkmcnt(1)
	v_cvt_pk_bf16_f32 v4, v2, v3
	ds_read2_b32 v[2:3], v5 offset0:138 offset1:203
	v_add_u32_e32 v5, 0x400, v22
	v_cvt_pk_bf16_f32 v0, v0, v1
	s_waitcnt lgkmcnt(1)
	v_cvt_pk_bf16_f32 v1, v6, v7
	ds_read2_b32 v[6:7], v5 offset0:4 offset1:69
	ds_read2_b32 v[12:13], v16 offset0:12 offset1:77
	ds_read2_b32 v[14:15], v5 offset0:134 offset1:199
	ds_read2_b32 v[16:17], v16 offset0:142 offset1:207
	s_waitcnt lgkmcnt(4)
	v_cvt_pk_bf16_f32 v5, v2, v3
	s_add_i32 s10, s10, s11
	s_add_i32 s14, s14, s15
	s_waitcnt lgkmcnt(3)
	v_cvt_pk_bf16_f32 v2, v6, v7
	s_waitcnt lgkmcnt(2)
	v_cvt_pk_bf16_f32 v6, v12, v13
	v_add_u32_e32 v12, s18, v21
	v_ashrrev_i32_e32 v13, 31, v12
	v_lshlrev_b64 v[12:13], 11, v[12:13]
	v_lshl_add_u64 v[12:13], s[4:5], 0, v[12:13]
	v_lshl_add_u64 v[12:13], v[12:13], 0, s[6:7]
	s_waitcnt lgkmcnt(1)
	v_cvt_pk_bf16_f32 v3, v14, v15
	s_waitcnt lgkmcnt(0)
	v_cvt_pk_bf16_f32 v7, v16, v17
	v_lshl_add_u64 v[12:13], v[12:13], 0, v[8:9]
	s_cmpk_lt_i32 s16, 0x80
	global_store_dwordx4 v[12:13], v[0:3], off
	global_store_dwordx4 v[12:13], v[4:7], off offset:64
	s_cbranch_scc0 .LBB0_523

.LBB0_523:
	v_readlane_b32 s0, v254, 10
	v_mov_b32_e32 v1, 0
	v_mov_b32_e32 v0, 0
	s_cmpk_gt_i32 s0, 0x17f
	v_readlane_b32 s1, v254, 11
	s_cbranch_scc1 .LBB0_526
	v_readlane_b32 s6, v254, 15
	v_readlane_b32 s7, v254, 16
	s_load_dwordx2 s[2:3], s[6:7], 0x98
	v_mbcnt_lo_u32_b32 v0, -1, v0
	v_mbcnt_hi_u32_b32 v0, -1, v0
	v_lshlrev_b32_e32 v7, 4, v0
	v_readlane_b32 s4, v254, 7
	v_and_b32_e32 v12, 48, v7
	v_lshrrev_b32_e32 v12, 1, v12
	s_add_u32 s0, s8, 0x2100000
	v_add_u32_e32 v6, s4, v0
	v_and_b32_e32 v0, 0xf0, v7
	v_mul_u32_u24_e32 v7, 0x41, v12
	v_ashrrev_i32_e32 v4, 4, v6
	s_waitcnt lgkmcnt(0)
	v_lshl_add_u64 v[2:3], s[2:3], 0, v[0:1]
	v_ashrrev_i32_e32 v5, 2, v6
	v_lshlrev_b32_e32 v7, 2, v7
	v_and_b32_e32 v6, -4, v6
	s_movk_i32 s2, 0x104
	v_add3_u32 v6, s91, v7, v6
	v_mul_lo_u32 v7, v4, s2
	s_load_dword s2, s[6:7], 0xb8
	s_addc_u32 s1, s9, 0
	v_add3_u32 v7, s91, v7, v0
	v_add_u32_e32 v8, 0x1040, v7
	v_add_u32_e32 v9, 0x2080, v7
	s_waitcnt lgkmcnt(0)
	s_lshl_b32 s5, s2, 7
	s_lshl_b32 s7, s2, 3
	v_add_u32_e32 v10, 0x30c0, v7
	s_lshl_b32 s4, s13, 6
	s_addk_i32 s5, 0xe000
	s_lshl_b32 s6, s13, 2
	s_addk_i32 s7, 0xfe00
	s_mov_b32 s3, 0
	v_lshlrev_b32_e32 v0, 1, v12
	v_add_u32_e32 v11, 0x2060, v6
	v_add_u32_e32 v12, 0x400, v6
	v_add_u32_e32 v13, 0x2460, v6
	s_mov_b32 s10, s13
.LBB0_525:
	s_and_b32 s11, s6, 0x7fffffc0
	v_add_u32_e32 v14, s11, v4
	s_and_b32 s14, s4, 0x3c0
	v_add_u32_e32 v16, 16, v14
	s_lshl_b32 s2, s14, 2
	v_ashrrev_i32_e32 v15, 31, v14
	v_add_u32_e32 v20, 32, v14
	v_add_u32_e32 v22, 48, v14
	v_ashrrev_i32_e32 v17, 31, v16
	v_lshl_add_u64 v[18:19], v[2:3], 0, s[2:3]
	v_lshlrev_b64 v[14:15], 12, v[14:15]
	v_ashrrev_i32_e32 v21, 31, v20
	v_ashrrev_i32_e32 v23, 31, v22
	v_lshlrev_b64 v[24:25], 12, v[16:17]
	v_lshl_add_u64 v[14:15], v[18:19], 0, v[14:15]
	v_lshlrev_b64 v[20:21], 12, v[20:21]
	v_lshlrev_b64 v[22:23], 12, v[22:23]
	v_lshl_add_u64 v[30:31], v[18:19], 0, v[24:25]
	s_barrier
	global_load_dwordx4 v[14:17], v[14:15], off
	v_lshl_add_u64 v[32:33], v[18:19], 0, v[20:21]
	v_lshl_add_u64 v[34:35], v[18:19], 0, v[22:23]
	global_load_dwordx4 v[18:21], v[30:31], off
	global_load_dwordx4 v[22:25], v[32:33], off
	global_load_dwordx4 v[26:29], v[34:35], off
	v_add_u32_e32 v30, s14, v5
	v_ashrrev_i32_e32 v31, 31, v30
	v_lshlrev_b64 v[30:31], 11, v[30:31]
	s_lshl_b32 s2, s11, 1
	v_lshl_add_u64 v[30:31], s[0:1], 0, v[30:31]
	s_add_i32 s10, s10, s12
	s_add_i32 s4, s4, s5
	s_add_i32 s6, s6, s7
	v_lshl_add_u64 v[30:31], v[30:31], 0, s[2:3]
	s_cmpk_lt_i32 s10, 0x100
	v_lshl_add_u64 v[30:31], v[30:31], 0, v[0:1]
	s_waitcnt vmcnt(3)
	ds_write2_b32 v7, v14, v15 offset1:1
	ds_write2_b32 v7, v16, v17 offset0:2 offset1:3
	s_waitcnt vmcnt(2)
	ds_write2_b32 v8, v18, v19 offset1:1
	ds_write2_b32 v8, v20, v21 offset0:2 offset1:3
	s_waitcnt vmcnt(1)
	ds_write2_b32 v9, v22, v23 offset1:1
	ds_write2_b32 v9, v24, v25 offset0:2 offset1:3
	s_waitcnt vmcnt(0)
	ds_write2_b32 v10, v26, v27 offset1:1
	ds_write2_b32 v10, v28, v29 offset0:2 offset1:3
	s_waitcnt lgkmcnt(0)
	s_barrier
	ds_read2_b32 v[14:15], v6 offset1:65
	ds_read2_b32 v[16:17], v11 offset0:8 offset1:73
	ds_read2_b32 v[20:21], v6 offset0:130 offset1:195
	ds_read2_b32 v[22:23], v11 offset0:138 offset1:203
	ds_read2_b32 v[24:25], v12 offset0:4 offset1:69
	ds_read2_b32 v[26:27], v13 offset0:12 offset1:77
	ds_read2_b32 v[28:29], v12 offset0:134 offset1:199
	ds_read2_b32 v[32:33], v13 offset0:142 offset1:207
	s_waitcnt lgkmcnt(7)
	v_cvt_pk_bf16_f32 v14, v14, v15
	s_waitcnt lgkmcnt(6)
	v_cvt_pk_bf16_f32 v18, v16, v17
	s_waitcnt lgkmcnt(5)
	v_cvt_pk_bf16_f32 v15, v20, v21
	s_waitcnt lgkmcnt(3)
	v_cvt_pk_bf16_f32 v16, v24, v25
	s_waitcnt lgkmcnt(1)
	v_cvt_pk_bf16_f32 v17, v28, v29
	v_cvt_pk_bf16_f32 v19, v22, v23
	v_cvt_pk_bf16_f32 v20, v26, v27
	s_waitcnt lgkmcnt(0)
	v_cvt_pk_bf16_f32 v21, v32, v33
	global_store_dwordx4 v[30:31], v[14:17], off
	global_store_dwordx4 v[30:31], v[18:21], off offset:64
	s_cbranch_scc1 .LBB0_525

.LBB0_528:
.LBB0_529:
	v_readlane_b32 s6, v254, 15
	v_readlane_b32 s7, v254, 16
	s_load_dwordx2 s[2:3], s[6:7], 0x90
	v_mbcnt_lo_u32_b32 v0, -1, v1
	v_mbcnt_hi_u32_b32 v0, -1, v0
	v_lshlrev_b32_e32 v7, 4, v0
	v_readlane_b32 s4, v254, 7
	v_and_b32_e32 v12, 48, v7
	v_lshrrev_b32_e32 v12, 1, v12
	v_mov_b32_e32 v1, 0
	v_add_u32_e32 v6, s4, v0
	v_and_b32_e32 v0, 0xf0, v7
	v_mul_u32_u24_e32 v7, 0x41, v12
	v_ashrrev_i32_e32 v4, 4, v6
	s_waitcnt lgkmcnt(0)
	v_lshl_add_u64 v[2:3], s[2:3], 0, v[0:1]
	v_ashrrev_i32_e32 v5, 2, v6
	v_lshlrev_b32_e32 v7, 2, v7
	v_and_b32_e32 v6, -4, v6
	s_movk_i32 s2, 0x104
	v_add3_u32 v6, s91, v7, v6
	v_mul_lo_u32 v7, v4, s2
	s_load_dword s2, s[6:7], 0xb8
	s_add_u32 s0, s8, 0x2500000
	s_addc_u32 s1, s9, 0
	v_add3_u32 v7, s91, v7, v0
	s_lshl_b32 s4, s13, 2
	s_waitcnt lgkmcnt(0)
	s_lshl_b32 s6, s2, 7
	s_lshl_b32 s7, s2, 3
	v_add_u32_e32 v8, 0x1040, v7
	v_add_u32_e32 v9, 0x2080, v7
	v_add_u32_e32 v10, 0x30c0, v7
	s_lshl_b32 s5, s13, 6
	s_addk_i32 s6, 0xe000
	s_addk_i32 s7, 0xfe00
	s_mov_b32 s3, 0
	v_lshlrev_b32_e32 v0, 1, v12
	v_add_u32_e32 v11, 0x2060, v6
	v_add_u32_e32 v12, 0x400, v6
	v_add_u32_e32 v13, 0x2460, v6
	s_mov_b32 s10, s4
	s_mov_b32 s11, s13
.LBB0_530:
	s_and_b32 s14, s10, 0x7fffffc0
	v_add_u32_e32 v14, s14, v4
	s_and_b32 s15, s5, 0x3c0
	v_add_u32_e32 v16, 16, v14
	s_lshl_b32 s2, s15, 2
	v_ashrrev_i32_e32 v15, 31, v14
	v_add_u32_e32 v20, 32, v14
	v_add_u32_e32 v22, 48, v14
	v_ashrrev_i32_e32 v17, 31, v16
	v_lshl_add_u64 v[18:19], v[2:3], 0, s[2:3]
	v_lshlrev_b64 v[14:15], 12, v[14:15]
	v_ashrrev_i32_e32 v21, 31, v20
	v_ashrrev_i32_e32 v23, 31, v22
	v_lshlrev_b64 v[24:25], 12, v[16:17]
	v_lshl_add_u64 v[14:15], v[18:19], 0, v[14:15]
	v_lshlrev_b64 v[20:21], 12, v[20:21]
	v_lshlrev_b64 v[22:23], 12, v[22:23]
	v_lshl_add_u64 v[30:31], v[18:19], 0, v[24:25]
	s_barrier
	global_load_dwordx4 v[14:17], v[14:15], off
	v_lshl_add_u64 v[32:33], v[18:19], 0, v[20:21]
	v_lshl_add_u64 v[34:35], v[18:19], 0, v[22:23]
	global_load_dwordx4 v[18:21], v[30:31], off
	global_load_dwordx4 v[22:25], v[32:33], off
	global_load_dwordx4 v[26:29], v[34:35], off
	v_add_u32_e32 v30, s15, v5
	v_ashrrev_i32_e32 v31, 31, v30
	v_lshlrev_b64 v[30:31], 9, v[30:31]
	s_lshl_b32 s2, s14, 1
	v_lshl_add_u64 v[30:31], s[0:1], 0, v[30:31]
	s_add_i32 s11, s11, s12
	s_add_i32 s5, s5, s6
	s_add_i32 s10, s10, s7
	v_lshl_add_u64 v[30:31], v[30:31], 0, s[2:3]
	s_cmp_lt_i32 s11, 64
	v_lshl_add_u64 v[30:31], v[30:31], 0, v[0:1]
	s_waitcnt vmcnt(3)
	ds_write2_b32 v7, v14, v15 offset1:1
	ds_write2_b32 v7, v16, v17 offset0:2 offset1:3
	s_waitcnt vmcnt(2)
	ds_write2_b32 v8, v18, v19 offset1:1
	ds_write2_b32 v8, v20, v21 offset0:2 offset1:3
	s_waitcnt vmcnt(1)
	ds_write2_b32 v9, v22, v23 offset1:1
	ds_write2_b32 v9, v24, v25 offset0:2 offset1:3
	s_waitcnt vmcnt(0)
	ds_write2_b32 v10, v26, v27 offset1:1
	ds_write2_b32 v10, v28, v29 offset0:2 offset1:3
	s_waitcnt lgkmcnt(0)
	s_barrier
	ds_read2_b32 v[14:15], v6 offset1:65
	ds_read2_b32 v[16:17], v11 offset0:8 offset1:73
	ds_read2_b32 v[20:21], v6 offset0:130 offset1:195
	ds_read2_b32 v[22:23], v11 offset0:138 offset1:203
	ds_read2_b32 v[24:25], v12 offset0:4 offset1:69
	ds_read2_b32 v[26:27], v13 offset0:12 offset1:77
	ds_read2_b32 v[28:29], v12 offset0:134 offset1:199
	ds_read2_b32 v[32:33], v13 offset0:142 offset1:207
	s_waitcnt lgkmcnt(7)
	v_cvt_pk_bf16_f32 v14, v14, v15
	s_waitcnt lgkmcnt(6)
	v_cvt_pk_bf16_f32 v18, v16, v17
	s_waitcnt lgkmcnt(5)
	v_cvt_pk_bf16_f32 v15, v20, v21
	s_waitcnt lgkmcnt(3)
	v_cvt_pk_bf16_f32 v16, v24, v25
	s_waitcnt lgkmcnt(1)
	v_cvt_pk_bf16_f32 v17, v28, v29
	v_cvt_pk_bf16_f32 v19, v22, v23
	v_cvt_pk_bf16_f32 v20, v26, v27
	s_waitcnt lgkmcnt(0)
	v_cvt_pk_bf16_f32 v21, v32, v33
	global_store_dwordx4 v[30:31], v[14:17], off
	global_store_dwordx4 v[30:31], v[18:21], off offset:64
	s_cbranch_scc1 .LBB0_530

.LBB0_1928:
	v_readlane_b32 s0, v254, 10
	v_readlane_b32 s48, v254, 30
	s_cmp_lt_i32 s0, s79
	v_readlane_b32 s91, v254, 17
	v_readlane_b32 s49, v254, 31
	v_readlane_b32 s1, v254, 11
	s_cbranch_scc1 .LBB0_1942
	v_mov_b32_e32 v1, 0
	v_mov_b32_e32 v0, 0
	s_cmpk_gt_i32 s33, 0x1ff
	s_cbranch_scc1 .LBB0_1932
	v_readlane_b32 s0, v254, 15
	v_readlane_b32 s1, v254, 16
	s_load_dwordx2 s[0:1], s[0:1], 0x88
	v_mbcnt_lo_u32_b32 v0, -1, v0
	v_mbcnt_hi_u32_b32 v0, -1, v0
	v_lshlrev_b32_e32 v7, 4, v0
	v_readlane_b32 s4, v254, 7
	v_and_b32_e32 v12, 48, v7
	v_lshrrev_b32_e32 v12, 1, v12
	s_add_u32 s2, s48, 0x1d00000
	v_add_u32_e32 v6, s4, v0
	v_and_b32_e32 v0, 0xf0, v7
	v_mul_u32_u24_e32 v7, 0x41, v12
	v_ashrrev_i32_e32 v4, 4, v6
	s_waitcnt lgkmcnt(0)
	v_lshl_add_u64 v[2:3], s[0:1], 0, v[0:1]
	v_ashrrev_i32_e32 v5, 2, v6
	v_lshlrev_b32_e32 v7, 2, v7
	v_and_b32_e32 v6, -4, v6
	s_movk_i32 s0, 0x104
	v_add3_u32 v6, s91, v7, v6
	v_mul_lo_u32 v7, v4, s0
	v_add3_u32 v7, s91, v7, v0
	s_addc_u32 s3, s49, 0
	v_add_u32_e32 v8, 0x1040, v7
	v_add_u32_e32 v9, 0x2080, v7
	v_add_u32_e32 v10, 0x30c0, v7
	s_lshl_b32 s0, s33, 6
	s_lshl_b32 s1, s79, 6
	v_lshlrev_b32_e32 v0, 1, v12
	v_add_u32_e32 v11, 0x2060, v6
	v_add_u32_e32 v12, 0x400, v6
	v_add_u32_e32 v13, 0x2460, v6
	s_mov_b32 s8, s33
.LBB0_1931:
	s_ashr_i32 s4, s8, 31
	s_lshr_b32 s4, s4, 28
	s_add_i32 s4, s8, s4
	s_ashr_i32 s5, s4, 4
	s_lshl_b32 s4, s5, 6
	s_lshl_b32 s5, s5, 10
	v_add_u32_e32 v14, s4, v4
	s_sub_i32 s6, s0, s5
	v_add_u32_e32 v16, 16, v14
	s_ashr_i32 s7, s6, 31
	v_ashrrev_i32_e32 v15, 31, v14
	v_add_u32_e32 v18, 32, v14
	v_add_u32_e32 v20, 48, v14
	v_ashrrev_i32_e32 v17, 31, v16
	v_lshl_add_u64 v[22:23], s[6:7], 2, v[2:3]
	v_lshlrev_b64 v[14:15], 12, v[14:15]
	v_ashrrev_i32_e32 v19, 31, v18
	v_ashrrev_i32_e32 v21, 31, v20
	v_lshlrev_b64 v[24:25], 12, v[16:17]
	v_lshl_add_u64 v[14:15], v[22:23], 0, v[14:15]
	v_lshlrev_b64 v[18:19], 12, v[18:19]
	v_lshlrev_b64 v[20:21], 12, v[20:21]
	v_lshl_add_u64 v[30:31], v[22:23], 0, v[24:25]
	s_waitcnt vmcnt(63) expcnt(7) lgkmcnt(15)
	s_barrier
	global_load_dwordx4 v[14:17], v[14:15], off
	v_lshl_add_u64 v[32:33], v[22:23], 0, v[18:19]
	v_lshl_add_u64 v[34:35], v[22:23], 0, v[20:21]
	global_load_dwordx4 v[18:21], v[30:31], off
	global_load_dwordx4 v[22:25], v[32:33], off
	global_load_dwordx4 v[26:29], v[34:35], off
	v_add_u32_e32 v30, s6, v5
	v_ashrrev_i32_e32 v31, 31, v30
	v_lshlrev_b64 v[30:31], 12, v[30:31]
	s_ashr_i32 s5, s4, 31
	v_lshl_add_u64 v[30:31], s[2:3], 0, v[30:31]
	s_add_i32 s8, s8, s79
	s_add_i32 s0, s0, s1
	v_lshl_add_u64 v[30:31], s[4:5], 1, v[30:31]
	s_cmpk_lt_i32 s8, 0x200
	v_lshl_add_u64 v[30:31], v[30:31], 0, v[0:1]
	s_waitcnt vmcnt(3)
	ds_write2_b32 v7, v14, v15 offset1:1
	ds_write2_b32 v7, v16, v17 offset0:2 offset1:3
	s_waitcnt vmcnt(2)
	ds_write2_b32 v8, v18, v19 offset1:1
	ds_write2_b32 v8, v20, v21 offset0:2 offset1:3
	s_waitcnt vmcnt(1)
	ds_write2_b32 v9, v22, v23 offset1:1
	ds_write2_b32 v9, v24, v25 offset0:2 offset1:3
	s_waitcnt vmcnt(0)
	ds_write2_b32 v10, v26, v27 offset1:1
	ds_write2_b32 v10, v28, v29 offset0:2 offset1:3
	s_waitcnt lgkmcnt(0)
	s_barrier
	ds_read2_b32 v[14:15], v6 offset1:65
	ds_read2_b32 v[16:17], v11 offset0:8 offset1:73
	ds_read2_b32 v[20:21], v6 offset0:130 offset1:195
	ds_read2_b32 v[22:23], v11 offset0:138 offset1:203
	ds_read2_b32 v[24:25], v12 offset0:4 offset1:69
	ds_read2_b32 v[26:27], v13 offset0:12 offset1:77
	ds_read2_b32 v[28:29], v12 offset0:134 offset1:199
	ds_read2_b32 v[32:33], v13 offset0:142 offset1:207
	s_waitcnt lgkmcnt(7)
	v_cvt_pk_bf16_f32 v14, v14, v15
	s_waitcnt lgkmcnt(6)
	v_cvt_pk_bf16_f32 v18, v16, v17
	s_waitcnt lgkmcnt(5)
	v_cvt_pk_bf16_f32 v15, v20, v21
	s_waitcnt lgkmcnt(3)
	v_cvt_pk_bf16_f32 v16, v24, v25
	s_waitcnt lgkmcnt(1)
	v_cvt_pk_bf16_f32 v17, v28, v29
	v_cvt_pk_bf16_f32 v19, v22, v23
	v_cvt_pk_bf16_f32 v20, v26, v27
	s_waitcnt lgkmcnt(0)
	v_cvt_pk_bf16_f32 v21, v32, v33
	global_store_dwordx4 v[30:31], v[14:17], off
	global_store_dwordx4 v[30:31], v[18:21], off offset:64
	s_cbranch_scc1 .LBB0_1931

.Lq9_1932:
	s_cmpk_gt_i32 s33, 0xff
	s_cbranch_scc1 .Lq9_1935
	v_readlane_b32 s0, v254, 15
	v_readlane_b32 s1, v254, 16
	s_load_dwordx2 s[0:1], s[0:1], 0x98
	v_mbcnt_lo_u32_b32 v0, -1, v1
	v_mbcnt_hi_u32_b32 v0, -1, v0
	v_readlane_b32 s4, v254, 7
	v_lshlrev_b32_e32 v7, 4, v0
	v_mov_b32_e32 v1, 0
	v_add_u32_e32 v6, s4, v0
	v_and_b32_e32 v0, 0xf0, v7
	v_and_b32_e32 v12, 48, v7
	v_lshrrev_b32_e32 v12, 1, v12
	s_waitcnt lgkmcnt(0)
	v_lshl_add_u64 v[2:3], s[0:1], 0, v[0:1]
	s_mov_b64 s[0:1], 0x400000
	v_mul_u32_u24_e32 v7, 0x41, v12
	v_ashrrev_i32_e32 v4, 4, v6
	v_lshl_add_u64 v[2:3], v[2:3], 0, s[0:1]
	v_ashrrev_i32_e32 v5, 2, v6
	v_lshlrev_b32_e32 v7, 2, v7
	v_and_b32_e32 v6, -4, v6
	s_movk_i32 s0, 0x104
	v_add3_u32 v6, s91, v7, v6
	v_mul_lo_u32 v7, v4, s0
	s_add_u32 s2, s48, 0x2300000
	v_add3_u32 v7, s91, v7, v0
	s_addc_u32 s3, s49, 0
	v_add_u32_e32 v8, 0x1040, v7
	v_add_u32_e32 v9, 0x2080, v7
	v_add_u32_e32 v10, 0x30c0, v7
	s_lshl_b32 s0, s33, 6
	s_lshl_b32 s1, s79, 6
	v_lshlrev_b32_e32 v0, 1, v12
	v_add_u32_e32 v11, 0x2060, v6
	v_add_u32_e32 v12, 0x400, v6
	v_add_u32_e32 v13, 0x2460, v6
	s_mov_b32 s8, s33
.Lq9_1934:
	s_ashr_i32 s4, s8, 31
	s_lshr_b32 s4, s4, 28
	s_add_i32 s4, s8, s4
	s_ashr_i32 s5, s4, 4
	s_lshl_b32 s4, s5, 6
	s_lshl_b32 s5, s5, 10
	v_add_u32_e32 v14, s4, v4
	s_sub_i32 s6, s0, s5
	v_add_u32_e32 v16, 16, v14
	s_ashr_i32 s7, s6, 31
	v_ashrrev_i32_e32 v15, 31, v14
	v_add_u32_e32 v18, 32, v14
	v_add_u32_e32 v20, 48, v14
	v_ashrrev_i32_e32 v17, 31, v16
	v_lshl_add_u64 v[22:23], s[6:7], 2, v[2:3]
	v_lshlrev_b64 v[14:15], 12, v[14:15]
	v_ashrrev_i32_e32 v19, 31, v18
	v_ashrrev_i32_e32 v21, 31, v20
	v_lshlrev_b64 v[24:25], 12, v[16:17]
	v_lshl_add_u64 v[14:15], v[22:23], 0, v[14:15]
	v_lshlrev_b64 v[18:19], 12, v[18:19]
	v_lshlrev_b64 v[20:21], 12, v[20:21]
	v_lshl_add_u64 v[30:31], v[22:23], 0, v[24:25]
	s_waitcnt vmcnt(63) expcnt(7) lgkmcnt(15)
	s_barrier
	global_load_dwordx4 v[14:17], v[14:15], off
	v_lshl_add_u64 v[32:33], v[22:23], 0, v[18:19]
	v_lshl_add_u64 v[34:35], v[22:23], 0, v[20:21]
	global_load_dwordx4 v[18:21], v[30:31], off
	global_load_dwordx4 v[22:25], v[32:33], off
	global_load_dwordx4 v[26:29], v[34:35], off
	v_add_u32_e32 v30, s6, v5
	v_ashrrev_i32_e32 v31, 31, v30
	v_lshlrev_b64 v[30:31], 11, v[30:31]
	s_ashr_i32 s5, s4, 31
	v_lshl_add_u64 v[30:31], s[2:3], 0, v[30:31]
	s_add_i32 s8, s8, s79
	s_add_i32 s0, s0, s1
	v_lshl_add_u64 v[30:31], s[4:5], 1, v[30:31]
	s_cmpk_lt_i32 s8, 0x100
	v_lshl_add_u64 v[30:31], v[30:31], 0, v[0:1]
	s_waitcnt vmcnt(3)
	ds_write2_b32 v7, v14, v15 offset1:1
	ds_write2_b32 v7, v16, v17 offset0:2 offset1:3
	s_waitcnt vmcnt(2)
	ds_write2_b32 v8, v18, v19 offset1:1
	ds_write2_b32 v8, v20, v21 offset0:2 offset1:3
	s_waitcnt vmcnt(1)
	ds_write2_b32 v9, v22, v23 offset1:1
	ds_write2_b32 v9, v24, v25 offset0:2 offset1:3
	s_waitcnt vmcnt(0)
	ds_write2_b32 v10, v26, v27 offset1:1
	ds_write2_b32 v10, v28, v29 offset0:2 offset1:3
	s_waitcnt lgkmcnt(0)
	s_barrier
	ds_read2_b32 v[14:15], v6 offset1:65
	ds_read2_b32 v[16:17], v11 offset0:8 offset1:73
	ds_read2_b32 v[20:21], v6 offset0:130 offset1:195
	ds_read2_b32 v[22:23], v11 offset0:138 offset1:203
	ds_read2_b32 v[24:25], v12 offset0:4 offset1:69
	ds_read2_b32 v[26:27], v13 offset0:12 offset1:77
	ds_read2_b32 v[28:29], v12 offset0:134 offset1:199
	ds_read2_b32 v[32:33], v13 offset0:142 offset1:207
	s_waitcnt lgkmcnt(7)
	v_cvt_pk_bf16_f32 v14, v14, v15
	s_waitcnt lgkmcnt(6)
	v_cvt_pk_bf16_f32 v18, v16, v17
	s_waitcnt lgkmcnt(5)
	v_cvt_pk_bf16_f32 v15, v20, v21
	s_waitcnt lgkmcnt(3)
	v_cvt_pk_bf16_f32 v16, v24, v25
	s_waitcnt lgkmcnt(1)
	v_cvt_pk_bf16_f32 v17, v28, v29
	v_cvt_pk_bf16_f32 v19, v22, v23
	v_cvt_pk_bf16_f32 v20, v26, v27
	s_waitcnt lgkmcnt(0)
	v_cvt_pk_bf16_f32 v21, v32, v33
	global_store_dwordx4 v[30:31], v[14:17], off
	global_store_dwordx4 v[30:31], v[18:21], off offset:64
	s_cbranch_scc1 .Lq9_1934
.Lq9_1935:
	v_mov_b32_e32 v1, 0
	v_mov_b32_e32 v0, 0
	s_cmp_gt_i32 s33, 63
	s_cbranch_scc1 .Lq9_1938
	v_readlane_b32 s0, v254, 15
	v_readlane_b32 s1, v254, 16
	s_load_dwordx2 s[0:1], s[0:1], 0x90
	v_mbcnt_lo_u32_b32 v0, -1, v0
	v_mbcnt_hi_u32_b32 v0, -1, v0
	v_readlane_b32 s4, v254, 7
	v_lshlrev_b32_e32 v7, 4, v0
	v_and_b32_e32 v12, 48, v7
	v_lshrrev_b32_e32 v12, 1, v12
	v_add_u32_e32 v6, s4, v0
	v_and_b32_e32 v0, 0xf0, v7
	s_waitcnt lgkmcnt(0)
	v_lshl_add_u64 v[2:3], s[0:1], 0, v[0:1]
	s_mov_b64 s[0:1], 0x100000
	v_mul_u32_u24_e32 v7, 0x41, v12
	v_ashrrev_i32_e32 v4, 4, v6
	v_lshl_add_u64 v[2:3], v[2:3], 0, s[0:1]
	v_ashrrev_i32_e32 v5, 2, v6
	v_lshlrev_b32_e32 v7, 2, v7
	v_and_b32_e32 v6, -4, v6
	s_movk_i32 s0, 0x104
	v_add3_u32 v6, s91, v7, v6
	v_mul_lo_u32 v7, v4, s0
	s_add_u32 s2, s48, 0x2580000
	v_add3_u32 v7, s91, v7, v0
	s_addc_u32 s3, s49, 0
	v_add_u32_e32 v8, 0x1040, v7
	v_add_u32_e32 v9, 0x2080, v7
	v_add_u32_e32 v10, 0x30c0, v7
	s_lshl_b32 s0, s33, 6
	s_lshl_b32 s1, s79, 6
	v_lshlrev_b32_e32 v0, 1, v12
	v_add_u32_e32 v11, 0x2060, v6
	v_add_u32_e32 v12, 0x400, v6
	v_add_u32_e32 v13, 0x2460, v6
	s_mov_b32 s8, s33
.Lq9_1937:
	s_ashr_i32 s4, s8, 31
	s_lshr_b32 s4, s4, 28
	s_add_i32 s4, s8, s4
	s_ashr_i32 s5, s4, 4
	s_lshl_b32 s4, s5, 6
	s_lshl_b32 s5, s5, 10
	v_add_u32_e32 v14, s4, v4
	s_sub_i32 s6, s0, s5
	v_add_u32_e32 v16, 16, v14
	s_ashr_i32 s7, s6, 31
	v_ashrrev_i32_e32 v15, 31, v14
	v_add_u32_e32 v18, 32, v14
	v_add_u32_e32 v20, 48, v14
	v_ashrrev_i32_e32 v17, 31, v16
	v_lshl_add_u64 v[22:23], s[6:7], 2, v[2:3]
	v_lshlrev_b64 v[14:15], 12, v[14:15]
	v_ashrrev_i32_e32 v19, 31, v18
	v_ashrrev_i32_e32 v21, 31, v20
	v_lshlrev_b64 v[24:25], 12, v[16:17]
	v_lshl_add_u64 v[14:15], v[22:23], 0, v[14:15]
	v_lshlrev_b64 v[18:19], 12, v[18:19]
	v_lshlrev_b64 v[20:21], 12, v[20:21]
	v_lshl_add_u64 v[30:31], v[22:23], 0, v[24:25]
	s_waitcnt vmcnt(63) expcnt(7) lgkmcnt(15)
	s_barrier
	global_load_dwordx4 v[14:17], v[14:15], off
	v_lshl_add_u64 v[32:33], v[22:23], 0, v[18:19]
	v_lshl_add_u64 v[34:35], v[22:23], 0, v[20:21]
	global_load_dwordx4 v[18:21], v[30:31], off
	global_load_dwordx4 v[22:25], v[32:33], off
	global_load_dwordx4 v[26:29], v[34:35], off
	v_add_u32_e32 v30, s6, v5
	v_ashrrev_i32_e32 v31, 31, v30
	v_lshlrev_b64 v[30:31], 9, v[30:31]
	s_ashr_i32 s5, s4, 31
	v_lshl_add_u64 v[30:31], s[2:3], 0, v[30:31]
	s_add_i32 s8, s8, s79
	s_add_i32 s0, s0, s1
	v_lshl_add_u64 v[30:31], s[4:5], 1, v[30:31]
	s_cmp_lt_i32 s8, 64
	v_lshl_add_u64 v[30:31], v[30:31], 0, v[0:1]
	s_waitcnt vmcnt(3)
	ds_write2_b32 v7, v14, v15 offset1:1
	ds_write2_b32 v7, v16, v17 offset0:2 offset1:3
	s_waitcnt vmcnt(2)
	ds_write2_b32 v8, v18, v19 offset1:1
	ds_write2_b32 v8, v20, v21 offset0:2 offset1:3
	s_waitcnt vmcnt(1)
	ds_write2_b32 v9, v22, v23 offset1:1
	ds_write2_b32 v9, v24, v25 offset0:2 offset1:3
	s_waitcnt vmcnt(0)
	ds_write2_b32 v10, v26, v27 offset1:1
	ds_write2_b32 v10, v28, v29 offset0:2 offset1:3
	s_waitcnt lgkmcnt(0)
	s_barrier
	ds_read2_b32 v[14:15], v6 offset1:65
	ds_read2_b32 v[16:17], v11 offset0:8 offset1:73
	ds_read2_b32 v[20:21], v6 offset0:130 offset1:195
	ds_read2_b32 v[22:23], v11 offset0:138 offset1:203
	ds_read2_b32 v[24:25], v12 offset0:4 offset1:69
	ds_read2_b32 v[26:27], v13 offset0:12 offset1:77
	ds_read2_b32 v[28:29], v12 offset0:134 offset1:199
	ds_read2_b32 v[32:33], v13 offset0:142 offset1:207
	s_waitcnt lgkmcnt(7)
	v_cvt_pk_bf16_f32 v14, v14, v15
	s_waitcnt lgkmcnt(6)
	v_cvt_pk_bf16_f32 v18, v16, v17
	s_waitcnt lgkmcnt(5)
	v_cvt_pk_bf16_f32 v15, v20, v21
	s_waitcnt lgkmcnt(3)
	v_cvt_pk_bf16_f32 v16, v24, v25
	s_waitcnt lgkmcnt(1)
	v_cvt_pk_bf16_f32 v17, v28, v29
	v_cvt_pk_bf16_f32 v19, v22, v23
	v_cvt_pk_bf16_f32 v20, v26, v27
	s_waitcnt lgkmcnt(0)
	v_cvt_pk_bf16_f32 v21, v32, v33
	global_store_dwordx4 v[30:31], v[14:17], off
	global_store_dwordx4 v[30:31], v[18:21], off offset:64
	s_cbranch_scc1 .Lq9_1937
